# N1 norm phase: all twelve per-row weight/scale/shift loads requested before the wave reduction; bf16 residual row halves requested together
# speedup vs baseline: 1.0173x; 1.0019x over previous
.LBB0_483:
	s_waitcnt vmcnt(3)
	v_pk_mul_f32 v[36:37], v[14:15], v[14:15]
	v_pk_mul_f32 v[38:39], v[16:17], v[16:17]
	v_add_f32_e32 v34, v37, v36
	v_add_f32_e32 v34, v38, v34
	s_waitcnt vmcnt(2)
	v_pk_mul_f32 v[44:45], v[10:11], v[10:11]
	v_add_f32_e32 v34, v39, v34
	v_add_f32_e32 v34, v44, v34
	v_pk_mul_f32 v[46:47], v[12:13], v[12:13]
	v_add_f32_e32 v34, v45, v34
	v_add_f32_e32 v34, v46, v34
	s_waitcnt vmcnt(1)
	v_pk_mul_f32 v[48:49], v[6:7], v[6:7]
	v_add_f32_e32 v34, v47, v34
	v_add_f32_e32 v34, v48, v34
	v_pk_mul_f32 v[50:51], v[8:9], v[8:9]
	v_add_f32_e32 v34, v49, v34
	v_add_f32_e32 v34, v50, v34
	s_waitcnt vmcnt(0)
	v_pk_mul_f32 v[52:53], v[2:3], v[2:3]
	v_add_f32_e32 v34, v51, v34
	v_add_f32_e32 v34, v52, v34
	v_pk_mul_f32 v[54:55], v[4:5], v[4:5]
	v_add_f32_e32 v34, v53, v34
	v_add_f32_e32 v34, v54, v34
	v_add_f32_e32 v34, v55, v34
	v_lshrrev_b32_e32 v31, 10, v31
	s_mul_i32 s8, s18, 5
	v_cmp_lt_i32_e32 vcc, s1, v18
	v_mov_b64_e32 v[36:37], s[86:87]
	s_nop 0
	v_cndmask_b32_e32 v31, 4, v31, vcc
	v_add_u32_e32 v31, s8, v31
	v_mad_i64_i32 v[36:37], s[26:27], v31, s82, v[36:37]
	s_mov_b64 s[26:27], 0x1000
	s_nop 0
	v_lshl_add_u64 v[38:39], v[36:37], 0, s[26:27]
	v_lshl_add_u64 v[56:57], v[38:39], 0, v[0:1]
	v_lshl_add_u64 v[36:37], v[36:37], 0, v[0:1]
	v_mov_b32_e32 v31, v1
	v_lshl_add_u64 v[38:39], v[38:39], 0, v[30:31]
	global_load_dwordx4 v[44:47], v[22:23], off offset:16
	global_load_dwordx4 v[48:51], v[22:23], off
	global_load_dwordx4 v[52:55], v[56:57], off offset:16
	s_nop 0
	global_load_dwordx4 v[56:59], v[56:57], off
	s_nop 0
	global_load_dwordx4 v[60:63], v[36:37], off offset:16
	global_load_dwordx4 v[64:67], v[36:37], off
	global_load_dwordx4 v[72:75], v[22:23], off offset:2064
	global_load_dwordx4 v[76:79], v[22:23], off offset:2048
	global_load_dwordx4 v[80:83], v[38:39], off offset:16
	global_load_dwordx4 v[84:87], v[38:39], off
	global_load_dwordx4 v[88:91], v[36:37], off offset:2064
	global_load_dwordx4 v[92:95], v[36:37], off offset:2048
	ds_bpermute_b32 v96, v21, v34
	v_lshl_add_u64 v[32:33], v[24:25], 0, v[32:33]
	s_waitcnt lgkmcnt(0)
	v_add_f32_e32 v34, v34, v96
	ds_bpermute_b32 v96, v35, v34
	s_waitcnt lgkmcnt(0)
	v_add_f32_e32 v34, v34, v96
	ds_bpermute_b32 v96, v40, v34
	s_waitcnt lgkmcnt(0)
	v_add_f32_e32 v34, v34, v96
	ds_bpermute_b32 v96, v41, v34
	s_waitcnt lgkmcnt(0)
	v_add_f32_e32 v34, v34, v96
	ds_bpermute_b32 v96, v42, v34
	s_waitcnt lgkmcnt(0)
	v_add_f32_e32 v34, v34, v96
	ds_bpermute_b32 v96, v43, v34
	s_waitcnt lgkmcnt(0)
	v_add_f32_e32 v34, v34, v96
	v_fmamk_f32 v34, v34, 0x3a800000, v205
	v_cmp_gt_f32_e32 vcc, s33, v34
	v_mul_f32_e32 v96, 0x4b800000, v34
	s_nop 0
	v_cndmask_b32_e32 v34, v34, v96, vcc
	v_rsq_f32_e32 v34, v34
	s_nop 0
	v_mul_f32_e32 v96, 0x45800000, v34
	v_cndmask_b32_e32 v34, v34, v96, vcc
	v_pk_mul_f32 v[10:11], v[10:11], v[34:35] op_sel_hi:[1,0]
	v_pk_mul_f32 v[14:15], v[14:15], v[34:35] op_sel_hi:[1,0]
	v_pk_mul_f32 v[16:17], v[16:17], v[34:35] op_sel_hi:[1,0]
	v_pk_mul_f32 v[2:3], v[2:3], v[34:35] op_sel_hi:[1,0]
	v_pk_mul_f32 v[6:7], v[6:7], v[34:35] op_sel_hi:[1,0]
	v_pk_mul_f32 v[8:9], v[8:9], v[34:35] op_sel_hi:[1,0]
	v_lshl_add_u64 v[18:19], v[18:19], 0, s[70:71]
	v_readlane_b32 s26, v255, 24
	v_readlane_b32 s27, v255, 25
	v_cmp_lt_i32_e32 vcc, s65, v18
	s_or_b64 s[24:25], vcc, s[24:25]
	v_lshl_add_u64 v[26:27], v[26:27], 0, s[26:27]
	s_waitcnt vmcnt(11)
	v_pk_mul_f32 v[10:11], v[44:45], v[10:11]
	s_waitcnt vmcnt(10)
	v_pk_mul_f32 v[14:15], v[48:49], v[14:15]
	s_waitcnt vmcnt(9)
	v_pk_add_f32 v[44:45], v[52:53], 1.0 op_sel_hi:[1,0]
	s_waitcnt vmcnt(8)
	v_pk_add_f32 v[48:49], v[56:57], 1.0 op_sel_hi:[1,0]
	s_waitcnt vmcnt(7)
	v_pk_fma_f32 v[44:45], v[44:45], v[10:11], v[60:61]
	v_pk_mul_f32 v[10:11], v[12:13], v[34:35] op_sel_hi:[1,0]
	s_waitcnt vmcnt(6)
	v_pk_fma_f32 v[14:15], v[48:49], v[14:15], v[64:65]
	v_pk_mul_f32 v[16:17], v[50:51], v[16:17]
	v_pk_add_f32 v[48:49], v[58:59], 1.0 op_sel_hi:[1,0]
	v_pk_mul_f32 v[10:11], v[46:47], v[10:11]
	v_pk_add_f32 v[12:13], v[54:55], 1.0 op_sel_hi:[1,0]
	v_pk_fma_f32 v[16:17], v[48:49], v[16:17], v[66:67]
	v_pk_fma_f32 v[46:47], v[12:13], v[10:11], v[62:63]
	v_cvt_pk_bf16_f32 v10, v14, v15
	v_cvt_pk_bf16_f32 v11, v16, v17
	v_cvt_pk_bf16_f32 v12, v44, v45
	v_cvt_pk_bf16_f32 v13, v46, v47
	global_store_dwordx4 v[32:33], v[10:13], off
	s_waitcnt vmcnt(6)
	v_pk_mul_f32 v[2:3], v[2:3], v[72:73]
	s_waitcnt vmcnt(5)
	v_pk_mul_f32 v[6:7], v[6:7], v[76:77]
	s_waitcnt vmcnt(4)
	v_pk_add_f32 v[10:11], v[80:81], 1.0 op_sel_hi:[1,0]
	s_waitcnt vmcnt(3)
	v_pk_add_f32 v[14:15], v[84:85], 1.0 op_sel_hi:[1,0]
	s_waitcnt vmcnt(2)
	v_pk_fma_f32 v[10:11], v[2:3], v[10:11], v[88:89]
	v_pk_mul_f32 v[2:3], v[4:5], v[34:35] op_sel_hi:[1,0]
	s_waitcnt vmcnt(1)
	v_pk_fma_f32 v[6:7], v[6:7], v[14:15], v[92:93]
	v_pk_mul_f32 v[8:9], v[8:9], v[78:79]
	v_pk_add_f32 v[14:15], v[86:87], 1.0 op_sel_hi:[1,0]
	v_pk_mul_f32 v[2:3], v[2:3], v[74:75]
	v_pk_add_f32 v[4:5], v[82:83], 1.0 op_sel_hi:[1,0]
	v_pk_fma_f32 v[8:9], v[8:9], v[14:15], v[94:95]
	v_pk_fma_f32 v[12:13], v[2:3], v[4:5], v[90:91]
	v_cvt_pk_bf16_f32 v2, v6, v7
	v_cvt_pk_bf16_f32 v3, v8, v9
	v_cvt_pk_bf16_f32 v4, v10, v11
	v_cvt_pk_bf16_f32 v5, v12, v13
	global_store_dwordx4 v[32:33], v[2:5], off offset:1024
	s_andn2_b64 exec, exec, s[24:25]
	s_cbranch_execz .LBB0_488
.LBB0_484:
	s_mov_b64 s[26:27], -1
	s_and_b64 vcc, exec, s[22:23]
	v_add_u32_e32 v34, 0xfffff000, v18
	s_cbranch_vccz .LBB0_486
	v_ashrrev_i32_e32 v3, 31, v18
	v_mov_b32_e32 v2, v18
	v_lshlrev_b64 v[32:33], 11, v[2:3]
	v_lshl_add_u64 v[2:3], v[28:29], 0, v[26:27]
	v_add_co_u32_e32 v6, vcc, 0x86b8000, v2
	v_add_u32_e32 v31, 0xfffff000, v18
	s_nop 0
	v_addc_co_u32_e32 v7, vcc, 0, v3, vcc
	global_load_dwordx4 v[68:71], v[6:7], off
	global_load_dwordx4 v[2:5], v[6:7], off offset:1024
	s_mov_b64 s[26:27], 0
	s_waitcnt vmcnt(1)
	v_lshlrev_b32_e32 v14, 16, v68
	v_and_b32_e32 v15, 0xffff0000, v68
	v_lshlrev_b32_e32 v16, 16, v69
	v_and_b32_e32 v17, 0xffff0000, v69
	v_lshlrev_b32_e32 v10, 16, v70
	v_and_b32_e32 v11, 0xffff0000, v70
	v_lshlrev_b32_e32 v12, 16, v71
	v_and_b32_e32 v13, 0xffff0000, v71
	s_waitcnt vmcnt(0)
	v_lshlrev_b32_e32 v6, 16, v2
	v_and_b32_e32 v7, 0xffff0000, v2
	v_lshlrev_b32_e32 v8, 16, v3
	v_and_b32_e32 v9, 0xffff0000, v3
	v_lshlrev_b32_e32 v2, 16, v4
	v_and_b32_e32 v3, 0xffff0000, v4
	v_lshlrev_b32_e32 v4, 16, v5
	v_and_b32_e32 v5, 0xffff0000, v5
